# GEMM slot table: global loads one slot ahead of the LDS writes (swapped tables), both spread over the MFMA sequence
# speedup vs baseline: 1.0188x; 1.0031x over previous
.Lgq_c:
	ds_read_b128 v[114:117], v188 offset:16384
	ds_read_b128 v[118:121], v188 offset:16896
	ds_read_b128 v[156:159], v188 offset:20480
	ds_read_b128 v[160:163], v188 offset:20992
	ds_read_b128 v[122:125], v112
	ds_read_b128 v[126:129], v112 offset:2048
	s_waitcnt lgkmcnt(1)
	v_mfma_f32_16x16x32_bf16 v[66:69], v[114:117], v[122:125], v[66:69]
	global_load_dwordx4 v[62:65], v216, s[0:1] offset:256
	v_mfma_f32_16x16x32_bf16 v[58:61], v[118:121], v[122:125], v[58:61]
	s_waitcnt vmcnt(8)
	ds_write_b128 v110, v[224:227] offset:32768
	v_mfma_f32_16x16x32_bf16 v[54:57], v[156:159], v[122:125], v[54:57]
	v_mfma_f32_16x16x32_bf16 v[50:53], v[160:163], v[122:125], v[50:53]
	global_load_dwordx4 v[70:73], v217, s[0:1] offset:256
	s_waitcnt lgkmcnt(1)
	v_mfma_f32_16x16x32_bf16 v[46:49], v[114:117], v[126:129], v[46:49]
	ds_read_b128 v[180:183], v112 offset:4096
	ds_read_b128 v[184:187], v112 offset:6144
	v_mfma_f32_16x16x32_bf16 v[42:45], v[118:121], v[126:129], v[42:45]
	s_waitcnt vmcnt(8)
	ds_write_b128 v110, v[228:231] offset:36864
	v_mfma_f32_16x16x32_bf16 v[38:41], v[156:159], v[126:129], v[38:41]
	global_load_dwordx4 v[74:77], v218, s[0:1] offset:256
	v_mfma_f32_16x16x32_bf16 v[34:37], v[160:163], v[126:129], v[34:37]
	s_waitcnt lgkmcnt(2)
	v_mfma_f32_16x16x32_bf16 v[30:33], v[114:117], v[180:183], v[30:33]
	ds_read_b128 v[164:167], v189 offset:16384
	ds_read_b128 v[168:171], v189 offset:16896
	v_mfma_f32_16x16x32_bf16 v[26:29], v[118:121], v[180:183], v[26:29]
	global_load_dwordx4 v[78:81], v219, s[0:1] offset:256
	v_mfma_f32_16x16x32_bf16 v[22:25], v[156:159], v[180:183], v[22:25]
	ds_read_b128 v[172:175], v189 offset:20480
	ds_read_b128 v[176:179], v189 offset:20992
	v_mfma_f32_16x16x32_bf16 v[18:21], v[160:163], v[180:183], v[18:21]
	s_waitcnt vmcnt(9)
	ds_write_b128 v110, v[232:235] offset:40960
	s_waitcnt lgkmcnt(6)
	v_mfma_f32_16x16x32_bf16 v[14:17], v[114:117], v[184:187], v[14:17]
	ds_read_b128 v[122:125], v113
	ds_read_b128 v[126:129], v113 offset:2048
	v_mfma_f32_16x16x32_bf16 v[10:13], v[118:121], v[184:187], v[10:13]
	global_load_dwordx4 v[82:85], v216, s[6:7] offset:256
	v_mfma_f32_16x16x32_bf16 v[6:9], v[156:159], v[184:187], v[6:9]
	s_waitcnt vmcnt(9)
	ds_write_b128 v110, v[236:239] offset:45056
	v_mfma_f32_16x16x32_bf16 v[2:5], v[160:163], v[184:187], v[2:5]
	s_waitcnt lgkmcnt(2)
	v_mfma_f32_16x16x32_bf16 v[66:69], v[164:167], v[122:125], v[66:69]
	global_load_dwordx4 v[86:89], v217, s[6:7] offset:256
	v_mfma_f32_16x16x32_bf16 v[58:61], v[168:171], v[122:125], v[58:61]
	s_waitcnt vmcnt(9)
	ds_write_b128 v190, v[240:243] offset:49168
	v_mfma_f32_16x16x32_bf16 v[54:57], v[172:175], v[122:125], v[54:57]
	v_mfma_f32_16x16x32_bf16 v[50:53], v[176:179], v[122:125], v[50:53]
	global_load_dwordx4 v[90:93], v218, s[6:7] offset:256
	s_waitcnt lgkmcnt(2)
	v_mfma_f32_16x16x32_bf16 v[46:49], v[164:167], v[126:129], v[46:49]
	ds_read_b128 v[180:183], v113 offset:4096
	ds_read_b128 v[184:187], v113 offset:6144
	v_mfma_f32_16x16x32_bf16 v[42:45], v[168:171], v[126:129], v[42:45]
	s_waitcnt vmcnt(9)
	ds_write_b128 v190, v[244:247] offset:53264
	v_mfma_f32_16x16x32_bf16 v[38:41], v[172:175], v[126:129], v[38:41]
	global_load_dwordx4 v[94:97], v219, s[6:7] offset:256
	v_mfma_f32_16x16x32_bf16 v[34:37], v[176:179], v[126:129], v[34:37]
	s_waitcnt lgkmcnt(2)
	v_mfma_f32_16x16x32_bf16 v[30:33], v[164:167], v[180:183], v[30:33]
	s_waitcnt vmcnt(9)
	ds_write_b128 v190, v[248:251] offset:57360
	v_mfma_f32_16x16x32_bf16 v[26:29], v[168:171], v[180:183], v[26:29]
	v_mfma_f32_16x16x32_bf16 v[22:25], v[172:175], v[180:183], v[22:25]
	v_mfma_f32_16x16x32_bf16 v[18:21], v[176:179], v[180:183], v[18:21]
	s_waitcnt vmcnt(8)
	ds_write_b128 v190, v[252:255] offset:61456
	s_waitcnt lgkmcnt(3)
	v_mfma_f32_16x16x32_bf16 v[14:17], v[164:167], v[184:187], v[14:17]
	v_mfma_f32_16x16x32_bf16 v[10:13], v[168:171], v[184:187], v[10:13]
	v_mfma_f32_16x16x32_bf16 v[6:9], v[172:175], v[184:187], v[6:9]
	v_mfma_f32_16x16x32_bf16 v[2:5], v[176:179], v[184:187], v[2:5]
	s_waitcnt lgkmcnt(0)
	s_barrier
	s_add_u32 s0, s0, 0x80
	s_addc_u32 s1, s1, 0
	s_add_u32 s6, s6, 0x80
	s_addc_u32 s7, s7, 0
	ds_read_b128 v[114:117], v188 offset:49168
	ds_read_b128 v[118:121], v188 offset:49680
	ds_read_b128 v[156:159], v188 offset:53264
	ds_read_b128 v[160:163], v188 offset:53776
	ds_read_b128 v[122:125], v112 offset:32768
	ds_read_b128 v[126:129], v112 offset:34816
	s_waitcnt lgkmcnt(1)
	v_mfma_f32_16x16x32_bf16 v[66:69], v[114:117], v[122:125], v[66:69]
	global_load_dwordx4 v[224:227], v216, s[0:1] offset:256
	v_mfma_f32_16x16x32_bf16 v[58:61], v[118:121], v[122:125], v[58:61]
	s_waitcnt vmcnt(8)
	ds_write_b128 v110, v[62:65]
	v_mfma_f32_16x16x32_bf16 v[54:57], v[156:159], v[122:125], v[54:57]
	v_mfma_f32_16x16x32_bf16 v[50:53], v[160:163], v[122:125], v[50:53]
	global_load_dwordx4 v[228:231], v217, s[0:1] offset:256
	s_waitcnt lgkmcnt(1)
	v_mfma_f32_16x16x32_bf16 v[46:49], v[114:117], v[126:129], v[46:49]
	ds_read_b128 v[180:183], v112 offset:36864
	ds_read_b128 v[184:187], v112 offset:38912
	v_mfma_f32_16x16x32_bf16 v[42:45], v[118:121], v[126:129], v[42:45]
	s_waitcnt vmcnt(8)
	ds_write_b128 v110, v[70:73] offset:4096
	v_mfma_f32_16x16x32_bf16 v[38:41], v[156:159], v[126:129], v[38:41]
	global_load_dwordx4 v[232:235], v218, s[0:1] offset:256
	v_mfma_f32_16x16x32_bf16 v[34:37], v[160:163], v[126:129], v[34:37]
	s_waitcnt lgkmcnt(2)
	v_mfma_f32_16x16x32_bf16 v[30:33], v[114:117], v[180:183], v[30:33]
	ds_read_b128 v[164:167], v189 offset:49168
	ds_read_b128 v[168:171], v189 offset:49680
	v_mfma_f32_16x16x32_bf16 v[26:29], v[118:121], v[180:183], v[26:29]
	global_load_dwordx4 v[236:239], v219, s[0:1] offset:256
	v_mfma_f32_16x16x32_bf16 v[22:25], v[156:159], v[180:183], v[22:25]
	ds_read_b128 v[172:175], v189 offset:53264
	ds_read_b128 v[176:179], v189 offset:53776
	v_mfma_f32_16x16x32_bf16 v[18:21], v[160:163], v[180:183], v[18:21]
	s_waitcnt vmcnt(9)
	ds_write_b128 v110, v[74:77] offset:8192
	s_waitcnt lgkmcnt(6)
	v_mfma_f32_16x16x32_bf16 v[14:17], v[114:117], v[184:187], v[14:17]
	ds_read_b128 v[122:125], v113 offset:32768
	ds_read_b128 v[126:129], v113 offset:34816
	v_mfma_f32_16x16x32_bf16 v[10:13], v[118:121], v[184:187], v[10:13]
	global_load_dwordx4 v[240:243], v216, s[6:7] offset:256
	v_mfma_f32_16x16x32_bf16 v[6:9], v[156:159], v[184:187], v[6:9]
	s_waitcnt vmcnt(9)
	ds_write_b128 v110, v[78:81] offset:12288
	v_mfma_f32_16x16x32_bf16 v[2:5], v[160:163], v[184:187], v[2:5]
	s_waitcnt lgkmcnt(2)
	v_mfma_f32_16x16x32_bf16 v[66:69], v[164:167], v[122:125], v[66:69]
	global_load_dwordx4 v[244:247], v217, s[6:7] offset:256
	v_mfma_f32_16x16x32_bf16 v[58:61], v[168:171], v[122:125], v[58:61]
	s_waitcnt vmcnt(9)
	ds_write_b128 v190, v[82:85] offset:16384
	v_mfma_f32_16x16x32_bf16 v[54:57], v[172:175], v[122:125], v[54:57]
	v_mfma_f32_16x16x32_bf16 v[50:53], v[176:179], v[122:125], v[50:53]
	global_load_dwordx4 v[248:251], v218, s[6:7] offset:256
	s_waitcnt lgkmcnt(2)
	v_mfma_f32_16x16x32_bf16 v[46:49], v[164:167], v[126:129], v[46:49]
	ds_read_b128 v[180:183], v113 offset:36864
	ds_read_b128 v[184:187], v113 offset:38912
	v_mfma_f32_16x16x32_bf16 v[42:45], v[168:171], v[126:129], v[42:45]
	s_waitcnt vmcnt(9)
	ds_write_b128 v190, v[86:89] offset:20480
	v_mfma_f32_16x16x32_bf16 v[38:41], v[172:175], v[126:129], v[38:41]
	global_load_dwordx4 v[252:255], v219, s[6:7] offset:256
	v_mfma_f32_16x16x32_bf16 v[34:37], v[176:179], v[126:129], v[34:37]
	s_waitcnt lgkmcnt(2)
	v_mfma_f32_16x16x32_bf16 v[30:33], v[164:167], v[180:183], v[30:33]
	s_waitcnt vmcnt(9)
	ds_write_b128 v190, v[90:93] offset:24576
	v_mfma_f32_16x16x32_bf16 v[26:29], v[168:171], v[180:183], v[26:29]
	v_mfma_f32_16x16x32_bf16 v[22:25], v[172:175], v[180:183], v[22:25]
	v_mfma_f32_16x16x32_bf16 v[18:21], v[176:179], v[180:183], v[18:21]
	s_waitcnt vmcnt(8)
	ds_write_b128 v190, v[94:97] offset:28672
	s_waitcnt lgkmcnt(3)
	v_mfma_f32_16x16x32_bf16 v[14:17], v[164:167], v[184:187], v[14:17]
	v_mfma_f32_16x16x32_bf16 v[10:13], v[168:171], v[184:187], v[10:13]
	v_mfma_f32_16x16x32_bf16 v[6:9], v[172:175], v[184:187], v[6:9]
	v_mfma_f32_16x16x32_bf16 v[2:5], v[176:179], v[184:187], v[2:5]
	s_waitcnt lgkmcnt(0)
	s_barrier
	s_add_u32 s0, s0, 0x80
	s_addc_u32 s1, s1, 0
	s_add_u32 s6, s6, 0x80
	s_addc_u32 s7, s7, 0
	s_sub_i32 vcc_lo, vcc_lo, 1
	s_cmp_lg_u32 vcc_lo, 0
	s_cbranch_scc1 .Lgq_c
	ds_read_b128 v[114:117], v188 offset:16384
	ds_read_b128 v[118:121], v188 offset:16896
	ds_read_b128 v[156:159], v188 offset:20480
	ds_read_b128 v[160:163], v188 offset:20992
	ds_read_b128 v[122:125], v112
	ds_read_b128 v[126:129], v112 offset:2048
	s_waitcnt lgkmcnt(1)
	v_mfma_f32_16x16x32_bf16 v[66:69], v[114:117], v[122:125], v[66:69]
	v_mfma_f32_16x16x32_bf16 v[58:61], v[118:121], v[122:125], v[58:61]
	s_waitcnt vmcnt(7)
	ds_write_b128 v110, v[224:227] offset:32768
	v_mfma_f32_16x16x32_bf16 v[54:57], v[156:159], v[122:125], v[54:57]
	v_mfma_f32_16x16x32_bf16 v[50:53], v[160:163], v[122:125], v[50:53]
	s_waitcnt lgkmcnt(1)
	v_mfma_f32_16x16x32_bf16 v[46:49], v[114:117], v[126:129], v[46:49]
	ds_read_b128 v[180:183], v112 offset:4096
	ds_read_b128 v[184:187], v112 offset:6144
	v_mfma_f32_16x16x32_bf16 v[42:45], v[118:121], v[126:129], v[42:45]
	s_waitcnt vmcnt(6)
	ds_write_b128 v110, v[228:231] offset:36864
	v_mfma_f32_16x16x32_bf16 v[38:41], v[156:159], v[126:129], v[38:41]
	v_mfma_f32_16x16x32_bf16 v[34:37], v[160:163], v[126:129], v[34:37]
	s_waitcnt lgkmcnt(2)
	v_mfma_f32_16x16x32_bf16 v[30:33], v[114:117], v[180:183], v[30:33]
	ds_read_b128 v[164:167], v189 offset:16384
	ds_read_b128 v[168:171], v189 offset:16896
	v_mfma_f32_16x16x32_bf16 v[26:29], v[118:121], v[180:183], v[26:29]
	v_mfma_f32_16x16x32_bf16 v[22:25], v[156:159], v[180:183], v[22:25]
	ds_read_b128 v[172:175], v189 offset:20480
	ds_read_b128 v[176:179], v189 offset:20992
	v_mfma_f32_16x16x32_bf16 v[18:21], v[160:163], v[180:183], v[18:21]
	s_waitcnt vmcnt(5)
	ds_write_b128 v110, v[232:235] offset:40960
	s_waitcnt lgkmcnt(6)
	v_mfma_f32_16x16x32_bf16 v[14:17], v[114:117], v[184:187], v[14:17]
	ds_read_b128 v[122:125], v113
	ds_read_b128 v[126:129], v113 offset:2048
	v_mfma_f32_16x16x32_bf16 v[10:13], v[118:121], v[184:187], v[10:13]
	v_mfma_f32_16x16x32_bf16 v[6:9], v[156:159], v[184:187], v[6:9]
	s_waitcnt vmcnt(4)
	ds_write_b128 v110, v[236:239] offset:45056
	v_mfma_f32_16x16x32_bf16 v[2:5], v[160:163], v[184:187], v[2:5]
	s_waitcnt lgkmcnt(2)
	v_mfma_f32_16x16x32_bf16 v[66:69], v[164:167], v[122:125], v[66:69]
	v_mfma_f32_16x16x32_bf16 v[58:61], v[168:171], v[122:125], v[58:61]
	s_waitcnt vmcnt(3)
	ds_write_b128 v190, v[240:243] offset:49168
	v_mfma_f32_16x16x32_bf16 v[54:57], v[172:175], v[122:125], v[54:57]
	v_mfma_f32_16x16x32_bf16 v[50:53], v[176:179], v[122:125], v[50:53]
	s_waitcnt lgkmcnt(2)
	v_mfma_f32_16x16x32_bf16 v[46:49], v[164:167], v[126:129], v[46:49]
	ds_read_b128 v[180:183], v113 offset:4096
	ds_read_b128 v[184:187], v113 offset:6144
	v_mfma_f32_16x16x32_bf16 v[42:45], v[168:171], v[126:129], v[42:45]
	s_waitcnt vmcnt(2)
	ds_write_b128 v190, v[244:247] offset:53264
	v_mfma_f32_16x16x32_bf16 v[38:41], v[172:175], v[126:129], v[38:41]
	v_mfma_f32_16x16x32_bf16 v[34:37], v[176:179], v[126:129], v[34:37]
	s_waitcnt lgkmcnt(2)
	v_mfma_f32_16x16x32_bf16 v[30:33], v[164:167], v[180:183], v[30:33]
	s_waitcnt vmcnt(1)
	ds_write_b128 v190, v[248:251] offset:57360
	v_mfma_f32_16x16x32_bf16 v[26:29], v[168:171], v[180:183], v[26:29]
	v_mfma_f32_16x16x32_bf16 v[22:25], v[172:175], v[180:183], v[22:25]
	v_mfma_f32_16x16x32_bf16 v[18:21], v[176:179], v[180:183], v[18:21]
	s_waitcnt vmcnt(0)
	ds_write_b128 v190, v[252:255] offset:61456
	s_waitcnt lgkmcnt(3)
	v_mfma_f32_16x16x32_bf16 v[14:17], v[164:167], v[184:187], v[14:17]
	v_mfma_f32_16x16x32_bf16 v[10:13], v[168:171], v[184:187], v[10:13]
	v_mfma_f32_16x16x32_bf16 v[6:9], v[172:175], v[184:187], v[6:9]
	v_mfma_f32_16x16x32_bf16 v[2:5], v[176:179], v[184:187], v[2:5]
	s_waitcnt lgkmcnt(0)
	s_barrier
	ds_read_b128 v[114:117], v188 offset:49168
	ds_read_b128 v[118:121], v188 offset:49680
	ds_read_b128 v[156:159], v188 offset:53264
	ds_read_b128 v[160:163], v188 offset:53776
	ds_read_b128 v[122:125], v112 offset:32768
	ds_read_b128 v[126:129], v112 offset:34816
	s_waitcnt lgkmcnt(1)
	v_mfma_f32_16x16x32_bf16 v[66:69], v[114:117], v[122:125], v[66:69]
	v_mfma_f32_16x16x32_bf16 v[58:61], v[118:121], v[122:125], v[58:61]
	v_mfma_f32_16x16x32_bf16 v[54:57], v[156:159], v[122:125], v[54:57]
	v_mfma_f32_16x16x32_bf16 v[50:53], v[160:163], v[122:125], v[50:53]
	s_waitcnt lgkmcnt(0)
	v_mfma_f32_16x16x32_bf16 v[46:49], v[114:117], v[126:129], v[46:49]
	ds_read_b128 v[180:183], v112 offset:36864
	ds_read_b128 v[184:187], v112 offset:38912
	v_mfma_f32_16x16x32_bf16 v[42:45], v[118:121], v[126:129], v[42:45]
	v_mfma_f32_16x16x32_bf16 v[38:41], v[156:159], v[126:129], v[38:41]
	v_mfma_f32_16x16x32_bf16 v[34:37], v[160:163], v[126:129], v[34:37]
	s_waitcnt lgkmcnt(1)
	v_mfma_f32_16x16x32_bf16 v[30:33], v[114:117], v[180:183], v[30:33]
	ds_read_b128 v[164:167], v189 offset:49168
	ds_read_b128 v[168:171], v189 offset:49680
	v_mfma_f32_16x16x32_bf16 v[26:29], v[118:121], v[180:183], v[26:29]
	v_mfma_f32_16x16x32_bf16 v[22:25], v[156:159], v[180:183], v[22:25]
	ds_read_b128 v[172:175], v189 offset:53264
	ds_read_b128 v[176:179], v189 offset:53776
	v_mfma_f32_16x16x32_bf16 v[18:21], v[160:163], v[180:183], v[18:21]
	s_waitcnt lgkmcnt(4)
	v_mfma_f32_16x16x32_bf16 v[14:17], v[114:117], v[184:187], v[14:17]
	ds_read_b128 v[122:125], v113 offset:32768
	ds_read_b128 v[126:129], v113 offset:34816
	v_mfma_f32_16x16x32_bf16 v[10:13], v[118:121], v[184:187], v[10:13]
	v_mfma_f32_16x16x32_bf16 v[6:9], v[156:159], v[184:187], v[6:9]
	v_mfma_f32_16x16x32_bf16 v[2:5], v[160:163], v[184:187], v[2:5]
	s_waitcnt lgkmcnt(1)
	v_mfma_f32_16x16x32_bf16 v[66:69], v[164:167], v[122:125], v[66:69]
	v_mfma_f32_16x16x32_bf16 v[58:61], v[168:171], v[122:125], v[58:61]
	v_mfma_f32_16x16x32_bf16 v[54:57], v[172:175], v[122:125], v[54:57]
	v_mfma_f32_16x16x32_bf16 v[50:53], v[176:179], v[122:125], v[50:53]
	s_waitcnt lgkmcnt(0)
	v_mfma_f32_16x16x32_bf16 v[46:49], v[164:167], v[126:129], v[46:49]
	ds_read_b128 v[180:183], v113 offset:36864
	ds_read_b128 v[184:187], v113 offset:38912
	v_mfma_f32_16x16x32_bf16 v[42:45], v[168:171], v[126:129], v[42:45]
	v_mfma_f32_16x16x32_bf16 v[38:41], v[172:175], v[126:129], v[38:41]
	v_mfma_f32_16x16x32_bf16 v[34:37], v[176:179], v[126:129], v[34:37]
	s_waitcnt lgkmcnt(1)
	v_mfma_f32_16x16x32_bf16 v[30:33], v[164:167], v[180:183], v[30:33]
	v_mfma_f32_16x16x32_bf16 v[26:29], v[168:171], v[180:183], v[26:29]
	v_mfma_f32_16x16x32_bf16 v[22:25], v[172:175], v[180:183], v[22:25]
	v_mfma_f32_16x16x32_bf16 v[18:21], v[176:179], v[180:183], v[18:21]
	s_waitcnt lgkmcnt(0)
	v_mfma_f32_16x16x32_bf16 v[14:17], v[164:167], v[184:187], v[14:17]
	v_mfma_f32_16x16x32_bf16 v[10:13], v[168:171], v[184:187], v[10:13]
	v_mfma_f32_16x16x32_bf16 v[6:9], v[172:175], v[184:187], v[6:9]
	v_mfma_f32_16x16x32_bf16 v[2:5], v[176:179], v[184:187], v[2:5]
	s_barrier

.Lgq_o:
	ds_read_b128 v[114:117], v188 offset:16384
	ds_read_b128 v[122:125], v188 offset:16896
	ds_read_b128 v[126:129], v188 offset:20480
	ds_read_b128 v[156:159], v188 offset:20992
	ds_read_b128 v[118:121], v112
	ds_read_b128 v[160:163], v112 offset:2048
	s_waitcnt lgkmcnt(1)
	v_mfma_f32_16x16x32_bf16 v[94:97], v[114:117], v[118:121], v[94:97]
	global_load_dwordx4 v[2:5], v216, s[10:11] offset:256
	v_mfma_f32_16x16x32_bf16 v[90:93], v[122:125], v[118:121], v[90:93]
	s_waitcnt vmcnt(8)
	ds_write_b128 v108, v[224:227] offset:32768
	v_mfma_f32_16x16x32_bf16 v[86:89], v[126:129], v[118:121], v[86:89]
	v_mfma_f32_16x16x32_bf16 v[82:85], v[156:159], v[118:121], v[82:85]
	global_load_dwordx4 v[6:9], v217, s[10:11] offset:256
	s_waitcnt lgkmcnt(1)
	v_mfma_f32_16x16x32_bf16 v[78:81], v[114:117], v[160:163], v[78:81]
	ds_read_b128 v[180:183], v112 offset:4096
	ds_read_b128 v[184:187], v112 offset:6144
	v_mfma_f32_16x16x32_bf16 v[74:77], v[122:125], v[160:163], v[74:77]
	s_waitcnt vmcnt(8)
	ds_write_b128 v108, v[228:231] offset:36864
	v_mfma_f32_16x16x32_bf16 v[70:73], v[126:129], v[160:163], v[70:73]
	global_load_dwordx4 v[10:13], v218, s[10:11] offset:256
	v_mfma_f32_16x16x32_bf16 v[66:69], v[156:159], v[160:163], v[66:69]
	s_waitcnt lgkmcnt(2)
	v_mfma_f32_16x16x32_bf16 v[62:65], v[114:117], v[180:183], v[62:65]
	ds_read_b128 v[164:167], v189 offset:16384
	ds_read_b128 v[168:171], v189 offset:16896
	v_mfma_f32_16x16x32_bf16 v[58:61], v[122:125], v[180:183], v[58:61]
	global_load_dwordx4 v[14:17], v219, s[10:11] offset:256
	v_mfma_f32_16x16x32_bf16 v[54:57], v[126:129], v[180:183], v[54:57]
	ds_read_b128 v[172:175], v189 offset:20480
	ds_read_b128 v[176:179], v189 offset:20992
	v_mfma_f32_16x16x32_bf16 v[50:53], v[156:159], v[180:183], v[50:53]
	s_waitcnt vmcnt(9)
	ds_write_b128 v108, v[232:235] offset:40960
	s_waitcnt lgkmcnt(6)
	v_mfma_f32_16x16x32_bf16 v[46:49], v[114:117], v[184:187], v[46:49]
	ds_read_b128 v[118:121], v113
	ds_read_b128 v[160:163], v113 offset:2048
	v_mfma_f32_16x16x32_bf16 v[42:45], v[122:125], v[184:187], v[42:45]
	global_load_dwordx4 v[18:21], v216, s[28:29] offset:256
	v_mfma_f32_16x16x32_bf16 v[38:41], v[126:129], v[184:187], v[38:41]
	s_waitcnt vmcnt(9)
	ds_write_b128 v108, v[236:239] offset:45056
	v_mfma_f32_16x16x32_bf16 v[34:37], v[156:159], v[184:187], v[34:37]
	s_waitcnt lgkmcnt(2)
	v_mfma_f32_16x16x32_bf16 v[94:97], v[164:167], v[118:121], v[94:97]
	global_load_dwordx4 v[22:25], v217, s[28:29] offset:256
	v_mfma_f32_16x16x32_bf16 v[90:93], v[168:171], v[118:121], v[90:93]
	s_waitcnt vmcnt(9)
	ds_write_b128 v190, v[240:243] offset:49168
	v_mfma_f32_16x16x32_bf16 v[86:89], v[172:175], v[118:121], v[86:89]
	v_mfma_f32_16x16x32_bf16 v[82:85], v[176:179], v[118:121], v[82:85]
	global_load_dwordx4 v[26:29], v218, s[28:29] offset:256
	s_waitcnt lgkmcnt(2)
	v_mfma_f32_16x16x32_bf16 v[78:81], v[164:167], v[160:163], v[78:81]
	ds_read_b128 v[180:183], v113 offset:4096
	ds_read_b128 v[184:187], v113 offset:6144
	v_mfma_f32_16x16x32_bf16 v[74:77], v[168:171], v[160:163], v[74:77]
	s_waitcnt vmcnt(9)
	ds_write_b128 v190, v[244:247] offset:53264
	v_mfma_f32_16x16x32_bf16 v[70:73], v[172:175], v[160:163], v[70:73]
	global_load_dwordx4 v[30:33], v219, s[28:29] offset:256
	v_mfma_f32_16x16x32_bf16 v[66:69], v[176:179], v[160:163], v[66:69]
	s_waitcnt lgkmcnt(2)
	v_mfma_f32_16x16x32_bf16 v[62:65], v[164:167], v[180:183], v[62:65]
	s_waitcnt vmcnt(9)
	ds_write_b128 v190, v[248:251] offset:57360
	v_mfma_f32_16x16x32_bf16 v[58:61], v[168:171], v[180:183], v[58:61]
	v_mfma_f32_16x16x32_bf16 v[54:57], v[172:175], v[180:183], v[54:57]
	v_mfma_f32_16x16x32_bf16 v[50:53], v[176:179], v[180:183], v[50:53]
	s_waitcnt vmcnt(8)
	ds_write_b128 v190, v[252:255] offset:61456
	s_waitcnt lgkmcnt(3)
	v_mfma_f32_16x16x32_bf16 v[46:49], v[164:167], v[184:187], v[46:49]
	v_mfma_f32_16x16x32_bf16 v[42:45], v[168:171], v[184:187], v[42:45]
	v_mfma_f32_16x16x32_bf16 v[38:41], v[172:175], v[184:187], v[38:41]
	v_mfma_f32_16x16x32_bf16 v[34:37], v[176:179], v[184:187], v[34:37]
	s_waitcnt lgkmcnt(0)
	s_barrier
	s_add_u32 s10, s10, 0x80
	s_addc_u32 s11, s11, 0
	s_add_u32 s28, s28, 0x80
	s_addc_u32 s29, s29, 0
	ds_read_b128 v[114:117], v188 offset:49168
	ds_read_b128 v[122:125], v188 offset:49680
	ds_read_b128 v[126:129], v188 offset:53264
	ds_read_b128 v[156:159], v188 offset:53776
	ds_read_b128 v[118:121], v112 offset:32768
	ds_read_b128 v[160:163], v112 offset:34816
	s_waitcnt lgkmcnt(1)
	v_mfma_f32_16x16x32_bf16 v[94:97], v[114:117], v[118:121], v[94:97]
	global_load_dwordx4 v[224:227], v216, s[10:11] offset:256
	v_mfma_f32_16x16x32_bf16 v[90:93], v[122:125], v[118:121], v[90:93]
	s_waitcnt vmcnt(8)
	ds_write_b128 v108, v[2:5]
	v_mfma_f32_16x16x32_bf16 v[86:89], v[126:129], v[118:121], v[86:89]
	v_mfma_f32_16x16x32_bf16 v[82:85], v[156:159], v[118:121], v[82:85]
	global_load_dwordx4 v[228:231], v217, s[10:11] offset:256
	s_waitcnt lgkmcnt(1)
	v_mfma_f32_16x16x32_bf16 v[78:81], v[114:117], v[160:163], v[78:81]
	ds_read_b128 v[180:183], v112 offset:36864
	ds_read_b128 v[184:187], v112 offset:38912
	v_mfma_f32_16x16x32_bf16 v[74:77], v[122:125], v[160:163], v[74:77]
	s_waitcnt vmcnt(8)
	ds_write_b128 v108, v[6:9] offset:4096
	v_mfma_f32_16x16x32_bf16 v[70:73], v[126:129], v[160:163], v[70:73]
	global_load_dwordx4 v[232:235], v218, s[10:11] offset:256
	v_mfma_f32_16x16x32_bf16 v[66:69], v[156:159], v[160:163], v[66:69]
	s_waitcnt lgkmcnt(2)
	v_mfma_f32_16x16x32_bf16 v[62:65], v[114:117], v[180:183], v[62:65]
	ds_read_b128 v[164:167], v189 offset:49168
	ds_read_b128 v[168:171], v189 offset:49680
	v_mfma_f32_16x16x32_bf16 v[58:61], v[122:125], v[180:183], v[58:61]
	global_load_dwordx4 v[236:239], v219, s[10:11] offset:256
	v_mfma_f32_16x16x32_bf16 v[54:57], v[126:129], v[180:183], v[54:57]
	ds_read_b128 v[172:175], v189 offset:53264
	ds_read_b128 v[176:179], v189 offset:53776
	v_mfma_f32_16x16x32_bf16 v[50:53], v[156:159], v[180:183], v[50:53]
	s_waitcnt vmcnt(9)
	ds_write_b128 v108, v[10:13] offset:8192
	s_waitcnt lgkmcnt(6)
	v_mfma_f32_16x16x32_bf16 v[46:49], v[114:117], v[184:187], v[46:49]
	ds_read_b128 v[118:121], v113 offset:32768
	ds_read_b128 v[160:163], v113 offset:34816
	v_mfma_f32_16x16x32_bf16 v[42:45], v[122:125], v[184:187], v[42:45]
	global_load_dwordx4 v[240:243], v216, s[28:29] offset:256
	v_mfma_f32_16x16x32_bf16 v[38:41], v[126:129], v[184:187], v[38:41]
	s_waitcnt vmcnt(9)
	ds_write_b128 v108, v[14:17] offset:12288
	v_mfma_f32_16x16x32_bf16 v[34:37], v[156:159], v[184:187], v[34:37]
	s_waitcnt lgkmcnt(2)
	v_mfma_f32_16x16x32_bf16 v[94:97], v[164:167], v[118:121], v[94:97]
	global_load_dwordx4 v[244:247], v217, s[28:29] offset:256
	v_mfma_f32_16x16x32_bf16 v[90:93], v[168:171], v[118:121], v[90:93]
	s_waitcnt vmcnt(9)
	ds_write_b128 v190, v[18:21] offset:16384
	v_mfma_f32_16x16x32_bf16 v[86:89], v[172:175], v[118:121], v[86:89]
	v_mfma_f32_16x16x32_bf16 v[82:85], v[176:179], v[118:121], v[82:85]
	global_load_dwordx4 v[248:251], v218, s[28:29] offset:256
	s_waitcnt lgkmcnt(2)
	v_mfma_f32_16x16x32_bf16 v[78:81], v[164:167], v[160:163], v[78:81]
	ds_read_b128 v[180:183], v113 offset:36864
	ds_read_b128 v[184:187], v113 offset:38912
	v_mfma_f32_16x16x32_bf16 v[74:77], v[168:171], v[160:163], v[74:77]
	s_waitcnt vmcnt(9)
	ds_write_b128 v190, v[22:25] offset:20480
	v_mfma_f32_16x16x32_bf16 v[70:73], v[172:175], v[160:163], v[70:73]
	global_load_dwordx4 v[252:255], v219, s[28:29] offset:256
	v_mfma_f32_16x16x32_bf16 v[66:69], v[176:179], v[160:163], v[66:69]
	s_waitcnt lgkmcnt(2)
	v_mfma_f32_16x16x32_bf16 v[62:65], v[164:167], v[180:183], v[62:65]
	s_waitcnt vmcnt(9)
	ds_write_b128 v190, v[26:29] offset:24576
	v_mfma_f32_16x16x32_bf16 v[58:61], v[168:171], v[180:183], v[58:61]
	v_mfma_f32_16x16x32_bf16 v[54:57], v[172:175], v[180:183], v[54:57]
	v_mfma_f32_16x16x32_bf16 v[50:53], v[176:179], v[180:183], v[50:53]
	s_waitcnt vmcnt(8)
	ds_write_b128 v190, v[30:33] offset:28672
	s_waitcnt lgkmcnt(3)
	v_mfma_f32_16x16x32_bf16 v[46:49], v[164:167], v[184:187], v[46:49]
	v_mfma_f32_16x16x32_bf16 v[42:45], v[168:171], v[184:187], v[42:45]
	v_mfma_f32_16x16x32_bf16 v[38:41], v[172:175], v[184:187], v[38:41]
	v_mfma_f32_16x16x32_bf16 v[34:37], v[176:179], v[184:187], v[34:37]
	s_waitcnt lgkmcnt(0)
	s_barrier
	s_add_u32 s10, s10, 0x80
	s_addc_u32 s11, s11, 0
	s_add_u32 s28, s28, 0x80
	s_addc_u32 s29, s29, 0
	s_sub_i32 vcc_lo, vcc_lo, 1
	s_cmp_lg_u32 vcc_lo, 0
	s_cbranch_scc1 .Lgq_o
	ds_read_b128 v[114:117], v188 offset:16384
	ds_read_b128 v[122:125], v188 offset:16896
	ds_read_b128 v[126:129], v188 offset:20480
	ds_read_b128 v[156:159], v188 offset:20992
	ds_read_b128 v[118:121], v112
	ds_read_b128 v[160:163], v112 offset:2048
	s_waitcnt lgkmcnt(1)
	v_mfma_f32_16x16x32_bf16 v[94:97], v[114:117], v[118:121], v[94:97]
	v_mfma_f32_16x16x32_bf16 v[90:93], v[122:125], v[118:121], v[90:93]
	s_waitcnt vmcnt(7)
	ds_write_b128 v108, v[224:227] offset:32768
	v_mfma_f32_16x16x32_bf16 v[86:89], v[126:129], v[118:121], v[86:89]
	v_mfma_f32_16x16x32_bf16 v[82:85], v[156:159], v[118:121], v[82:85]
	s_waitcnt lgkmcnt(1)
	v_mfma_f32_16x16x32_bf16 v[78:81], v[114:117], v[160:163], v[78:81]
	ds_read_b128 v[180:183], v112 offset:4096
	ds_read_b128 v[184:187], v112 offset:6144
	v_mfma_f32_16x16x32_bf16 v[74:77], v[122:125], v[160:163], v[74:77]
	s_waitcnt vmcnt(6)
	ds_write_b128 v108, v[228:231] offset:36864
	v_mfma_f32_16x16x32_bf16 v[70:73], v[126:129], v[160:163], v[70:73]
	v_mfma_f32_16x16x32_bf16 v[66:69], v[156:159], v[160:163], v[66:69]
	s_waitcnt lgkmcnt(2)
	v_mfma_f32_16x16x32_bf16 v[62:65], v[114:117], v[180:183], v[62:65]
	ds_read_b128 v[164:167], v189 offset:16384
	ds_read_b128 v[168:171], v189 offset:16896
	v_mfma_f32_16x16x32_bf16 v[58:61], v[122:125], v[180:183], v[58:61]
	v_mfma_f32_16x16x32_bf16 v[54:57], v[126:129], v[180:183], v[54:57]
	ds_read_b128 v[172:175], v189 offset:20480
	ds_read_b128 v[176:179], v189 offset:20992
	v_mfma_f32_16x16x32_bf16 v[50:53], v[156:159], v[180:183], v[50:53]
	s_waitcnt vmcnt(5)
	ds_write_b128 v108, v[232:235] offset:40960
	s_waitcnt lgkmcnt(6)
	v_mfma_f32_16x16x32_bf16 v[46:49], v[114:117], v[184:187], v[46:49]
	ds_read_b128 v[118:121], v113
	ds_read_b128 v[160:163], v113 offset:2048
	v_mfma_f32_16x16x32_bf16 v[42:45], v[122:125], v[184:187], v[42:45]
	v_mfma_f32_16x16x32_bf16 v[38:41], v[126:129], v[184:187], v[38:41]
	s_waitcnt vmcnt(4)
	ds_write_b128 v108, v[236:239] offset:45056
	v_mfma_f32_16x16x32_bf16 v[34:37], v[156:159], v[184:187], v[34:37]
	s_waitcnt lgkmcnt(2)
	v_mfma_f32_16x16x32_bf16 v[94:97], v[164:167], v[118:121], v[94:97]
	v_mfma_f32_16x16x32_bf16 v[90:93], v[168:171], v[118:121], v[90:93]
	s_waitcnt vmcnt(3)
	ds_write_b128 v190, v[240:243] offset:49168
	v_mfma_f32_16x16x32_bf16 v[86:89], v[172:175], v[118:121], v[86:89]
	v_mfma_f32_16x16x32_bf16 v[82:85], v[176:179], v[118:121], v[82:85]
	s_waitcnt lgkmcnt(2)
	v_mfma_f32_16x16x32_bf16 v[78:81], v[164:167], v[160:163], v[78:81]
	ds_read_b128 v[180:183], v113 offset:4096
	ds_read_b128 v[184:187], v113 offset:6144
	v_mfma_f32_16x16x32_bf16 v[74:77], v[168:171], v[160:163], v[74:77]
	s_waitcnt vmcnt(2)
	ds_write_b128 v190, v[244:247] offset:53264
	v_mfma_f32_16x16x32_bf16 v[70:73], v[172:175], v[160:163], v[70:73]
	v_mfma_f32_16x16x32_bf16 v[66:69], v[176:179], v[160:163], v[66:69]
	s_waitcnt lgkmcnt(2)
	v_mfma_f32_16x16x32_bf16 v[62:65], v[164:167], v[180:183], v[62:65]
	s_waitcnt vmcnt(1)
	ds_write_b128 v190, v[248:251] offset:57360
	v_mfma_f32_16x16x32_bf16 v[58:61], v[168:171], v[180:183], v[58:61]
	v_mfma_f32_16x16x32_bf16 v[54:57], v[172:175], v[180:183], v[54:57]
	v_mfma_f32_16x16x32_bf16 v[50:53], v[176:179], v[180:183], v[50:53]
	s_waitcnt vmcnt(0)
	ds_write_b128 v190, v[252:255] offset:61456
	s_waitcnt lgkmcnt(3)
	v_mfma_f32_16x16x32_bf16 v[46:49], v[164:167], v[184:187], v[46:49]
	v_mfma_f32_16x16x32_bf16 v[42:45], v[168:171], v[184:187], v[42:45]
	v_mfma_f32_16x16x32_bf16 v[38:41], v[172:175], v[184:187], v[38:41]
	v_mfma_f32_16x16x32_bf16 v[34:37], v[176:179], v[184:187], v[34:37]
	s_waitcnt lgkmcnt(0)
	s_barrier
	ds_read_b128 v[114:117], v188 offset:49168
	ds_read_b128 v[122:125], v188 offset:49680
	ds_read_b128 v[126:129], v188 offset:53264
	ds_read_b128 v[156:159], v188 offset:53776
	ds_read_b128 v[118:121], v112 offset:32768
	ds_read_b128 v[160:163], v112 offset:34816
	s_waitcnt lgkmcnt(1)
	v_mfma_f32_16x16x32_bf16 v[94:97], v[114:117], v[118:121], v[94:97]
	v_mfma_f32_16x16x32_bf16 v[90:93], v[122:125], v[118:121], v[90:93]
	v_mfma_f32_16x16x32_bf16 v[86:89], v[126:129], v[118:121], v[86:89]
	v_mfma_f32_16x16x32_bf16 v[82:85], v[156:159], v[118:121], v[82:85]
	s_waitcnt lgkmcnt(0)
	v_mfma_f32_16x16x32_bf16 v[78:81], v[114:117], v[160:163], v[78:81]
	ds_read_b128 v[180:183], v112 offset:36864
	ds_read_b128 v[184:187], v112 offset:38912
	v_mfma_f32_16x16x32_bf16 v[74:77], v[122:125], v[160:163], v[74:77]
	v_mfma_f32_16x16x32_bf16 v[70:73], v[126:129], v[160:163], v[70:73]
	v_mfma_f32_16x16x32_bf16 v[66:69], v[156:159], v[160:163], v[66:69]
	s_waitcnt lgkmcnt(1)
	v_mfma_f32_16x16x32_bf16 v[62:65], v[114:117], v[180:183], v[62:65]
	ds_read_b128 v[164:167], v189 offset:49168
	ds_read_b128 v[168:171], v189 offset:49680
	v_mfma_f32_16x16x32_bf16 v[58:61], v[122:125], v[180:183], v[58:61]
	v_mfma_f32_16x16x32_bf16 v[54:57], v[126:129], v[180:183], v[54:57]
	ds_read_b128 v[172:175], v189 offset:53264
	ds_read_b128 v[176:179], v189 offset:53776
	v_mfma_f32_16x16x32_bf16 v[50:53], v[156:159], v[180:183], v[50:53]
	s_waitcnt lgkmcnt(4)
	v_mfma_f32_16x16x32_bf16 v[46:49], v[114:117], v[184:187], v[46:49]
	ds_read_b128 v[118:121], v113 offset:32768
	ds_read_b128 v[160:163], v113 offset:34816
	v_mfma_f32_16x16x32_bf16 v[42:45], v[122:125], v[184:187], v[42:45]
	v_mfma_f32_16x16x32_bf16 v[38:41], v[126:129], v[184:187], v[38:41]
	v_mfma_f32_16x16x32_bf16 v[34:37], v[156:159], v[184:187], v[34:37]
	s_waitcnt lgkmcnt(1)
	v_mfma_f32_16x16x32_bf16 v[94:97], v[164:167], v[118:121], v[94:97]
	v_mfma_f32_16x16x32_bf16 v[90:93], v[168:171], v[118:121], v[90:93]
	v_mfma_f32_16x16x32_bf16 v[86:89], v[172:175], v[118:121], v[86:89]
	v_mfma_f32_16x16x32_bf16 v[82:85], v[176:179], v[118:121], v[82:85]
	s_waitcnt lgkmcnt(0)
	v_mfma_f32_16x16x32_bf16 v[78:81], v[164:167], v[160:163], v[78:81]
	ds_read_b128 v[180:183], v113 offset:36864
	ds_read_b128 v[184:187], v113 offset:38912
	v_mfma_f32_16x16x32_bf16 v[74:77], v[168:171], v[160:163], v[74:77]
	v_mfma_f32_16x16x32_bf16 v[70:73], v[172:175], v[160:163], v[70:73]
	v_mfma_f32_16x16x32_bf16 v[66:69], v[176:179], v[160:163], v[66:69]
	s_waitcnt lgkmcnt(1)
	v_mfma_f32_16x16x32_bf16 v[62:65], v[164:167], v[180:183], v[62:65]
	v_mfma_f32_16x16x32_bf16 v[58:61], v[168:171], v[180:183], v[58:61]
	v_mfma_f32_16x16x32_bf16 v[54:57], v[172:175], v[180:183], v[54:57]
	v_mfma_f32_16x16x32_bf16 v[50:53], v[176:179], v[180:183], v[50:53]
	s_waitcnt lgkmcnt(0)
	v_mfma_f32_16x16x32_bf16 v[46:49], v[164:167], v[184:187], v[46:49]
	v_mfma_f32_16x16x32_bf16 v[42:45], v[168:171], v[184:187], v[42:45]
	v_mfma_f32_16x16x32_bf16 v[38:41], v[172:175], v[184:187], v[38:41]
	v_mfma_f32_16x16x32_bf16 v[34:37], v[176:179], v[184:187], v[34:37]
	s_barrier
	s_branch .LBB0_1383
